# P1->GEMM1 local seam also uses the L1-only invalidate: phase-0 outputs are written through and were never fetched by this XCD before, so no stale L2 line can exist
# speedup vs baseline: 1.0018x; 1.0018x over previous
; __device__ __forceinline__ unsigned xb_ld(unsigned* p)              { return __hip_atomic_load(p, __ATOMIC_RELAXED, __HIP_MEMORY_SCOPE_AGENT); }
; __device__ __forceinline__ unsigned xb_add(unsigned* p, unsigned v) { return __hip_atomic_fetch_add(p, v, __ATOMIC_RELAXED, __HIP_MEMORY_SCOPE_AGENT); }
; #define XB_SPIN(cond, bar) do { unsigned _sp = 0; while (cond) { __builtin_amdgcn_s_sleep(1); \
;     if ((++_sp & 255u) == 0u) { if (xb_ld(&(bar)[XB_TMO])) break; if (_sp > XB_SPIN_CAP) { atomicAdd(&(bar)[XB_TMO], 1u); break; } } } } while (0)
; __device__ __forceinline__ void xcd_barrier(const XcdBarrier& b) {
;     asm volatile("s_waitcnt vmcnt(0)" ::: "memory");
;     __syncthreads();
;     if (threadIdx.x == 0) {
;         unsigned* bar = b.bar;
;         __builtin_amdgcn_s_waitcnt(0);
;         unsigned nloc = b.st[0], nx = b.st[1];
;         if (nloc == 0u) { xcd_barrier_complete(bar, b.x, nloc, nx); b.st[0] = nloc; b.st[1] = nx; }
;         const unsigned old = xb_add(&bar[XB_XSUB(b.x)], 1u);
;         const unsigned gen = old / nloc;
;         if (old + 1u == (gen + 1u) * nloc) {
;             __builtin_amdgcn_fence(__ATOMIC_RELEASE, "agent");
;             asm volatile("s_waitcnt vmcnt(0)" ::: "memory");
;             const unsigned og = xb_add(&bar[XB_TOP], 1u);
;             const unsigned tg = og / nx;
;             if (og + 1u == (tg + 1u) * nx) xb_add(&bar[XB_TOPGEN], 1u);
;             else XB_SPIN(xb_ld(&bar[XB_TOPGEN]) == tg, bar);
;             __builtin_amdgcn_fence(__ATOMIC_ACQUIRE, "agent");
;             xb_add(&bar[XB_XGEN(b.x)], 1u);
;             asm volatile("s_waitcnt vmcnt(0)" ::: "memory");
;         } else {
;             XB_SPIN(xb_ld(&bar[XB_XGEN(b.x)]) == gen, bar);
;             __builtin_amdgcn_fence(__ATOMIC_ACQUIRE, "agent");
;             asm volatile("s_waitcnt vmcnt(0)" ::: "memory");
;         }
;     }
;     __syncthreads();
.Lfb_md_1:
	v_cmp_le_u32_e32 vcc, 0x100, v4
	s_cbranch_vccnz .Lfb_done_1
	global_load_dword v4, v3, s[90:91] sc1
	v_add_u32_e32 v2, 1, v2
	s_waitcnt vmcnt(0)
	v_cmp_gt_u32_e32 vcc, 0x10000, v2
	s_cbranch_vccnz .Lfb_md_1
.Lfb_done_1:
	buffer_inv sc0
	s_waitcnt vmcnt(0)
	s_branch .LBB0_338
